# attention tile loop: -m kept in a register pair (updated only in the new-maximum path), per-tile accumulator fill starts with one 64-bit move instead of xor+mov
# baseline (speedup 1.0000x reference)
.LBB0_422:
	s_lshl_b32 s0, s39, 10
	s_and_b32 s6, s0, 0x800000
	s_lshl_b32 s0, s43, 1
	s_and_b32 s66, s0, 0x300
	s_lshl_b32 s0, s64, 11
	s_lshl_b32 s1, s64, 4
	s_and_b32 s0, s0, 0x2000
	s_and_b32 s1, s1, 0xffffff80
	s_add_i32 s1, s0, s1
	v_or_b32_e32 v171, s1, v170
	v_or_b32_e32 v0, v171, v169
	v_ashrrev_i32_e32 v1, 31, v0
	s_lshl_b32 s1, s64, 7
	v_lshlrev_b64 v[0:1], 10, v[0:1]
	s_and_b32 s65, s1, 0x180
	v_lshl_add_u64 v[0:1], s[86:87], 0, v[0:1]
	s_lshl_b32 s4, s65, 1
	s_mov_b32 s5, s7
	v_lshl_add_u64 v[0:1], v[0:1], 0, s[4:5]
	s_lshl_b32 s5, s0, 10
	s_add_u32 s0, s33, s5
	s_addc_u32 s1, s34, 0
	s_add_u32 s0, s0, s4
	v_mov_b32_e32 v174, v168
	v_lshl_add_u64 v[0:1], v[160:161], 1, v[0:1]
	s_addc_u32 s1, s1, 0
	v_lshl_add_u64 v[0:1], v[0:1], 0, v[162:163]
	v_ashrrev_i32_e32 v16, 4, v174
	s_add_u32 s5, s35, s5
	v_lshlrev_b32_e32 v20, 3, v174
	v_add_u32_e32 v18, 32, v16
	s_addc_u32 s16, s38, 0
	global_load_dwordx4 v[124:127], v[0:1], off
	global_load_dwordx4 v[120:123], v[0:1], off offset:32
	global_load_dwordx4 v[116:119], v[0:1], off offset:64
	global_load_dwordx4 v[112:115], v[0:1], off offset:96
	v_and_b32_e32 v0, 0x78, v20
	v_ashrrev_i32_e32 v17, 31, v16
	v_ashrrev_i32_e32 v19, 31, v18
	s_add_u32 s4, s5, s4
	v_lshlrev_b32_e32 v21, 1, v0
	v_lshlrev_b64 v[48:49], 10, v[16:17]
	v_lshlrev_b64 v[12:13], 10, v[18:19]
	s_addc_u32 s5, s16, 0
	v_or_b32_e32 v50, v48, v21
	v_mov_b32_e32 v51, v49
	v_or_b32_e32 v12, v12, v21
	v_lshl_add_u64 v[0:1], s[4:5], 0, v[50:51]
	v_lshl_add_u64 v[4:5], s[4:5], 0, v[12:13]
	s_barrier
	global_load_dwordx4 v[0:3], v[0:1], off
	s_nop 0
	global_load_dwordx4 v[4:7], v[4:5], off
	v_lshl_add_u64 v[8:9], s[0:1], 0, v[50:51]
	global_load_dwordx4 v[8:11], v[8:9], off
	v_lshl_add_u64 v[12:13], s[0:1], 0, v[12:13]
	global_load_dwordx4 v[12:15], v[12:13], off
	v_and_b32_e32 v22, 0xfffff0, v16
	v_lshlrev_b32_e32 v23, 1, v16
	v_lshrrev_b32_e32 v24, 1, v16
	v_and_b32_e32 v25, 3, v16
	v_and_or_b32 v22, v23, 8, v22
	v_and_or_b32 v23, v24, 4, v25
	v_and_b32_e32 v24, 0xfffff0, v18
	v_lshlrev_b32_e32 v25, 1, v18
	v_and_b32_e32 v17, 0x70, v174
	v_bfe_u32 v20, v20, 5, 2
	v_lshlrev_b32_e32 v16, 8, v16
	v_lshrrev_b32_e32 v22, 1, v22
	v_and_or_b32 v24, v25, 8, v24
	v_bitop3_b32 v183, v21, v16, v17 bitop3:0xde
	v_or_b32_e32 v16, v22, v20
	v_lshrrev_b32_e32 v22, 1, v24
	v_lshlrev_b32_e32 v23, 6, v23
	v_and_b32_e32 v26, 48, v21
	v_lshlrev_b32_e32 v16, 9, v16
	v_or_b32_e32 v20, v22, v20
	v_or3_b32 v184, v16, v23, v26
	v_lshlrev_b32_e32 v16, 9, v20
	v_bfe_u32 v172, v174, 5, 1
	v_ashrrev_i32_e32 v175, 8, v174
	v_lshlrev_b32_e32 v52, 4, v174
	v_or3_b32 v186, v16, v23, v26
	v_add_u32_e32 v84, 16, v184
	v_and_b32_e32 v173, 31, v174
	v_lshlrev_b32_e32 v19, 7, v175
	v_add_u32_e32 v24, 16, v183
	v_add_u32_e32 v85, 16, v186
	s_waitcnt vmcnt(0)
	v_lshlrev_b32_e32 v176, 4, v172
	v_lshlrev_b32_e32 v190, 8, v173
	v_and_b32_e32 v86, 63, v174
	v_lshl_add_u64 v[60:61], v[50:51], 0, s[14:15]
	v_lshl_add_u64 v[64:65], v[50:51], 0, s[36:37]
	v_lshl_add_u64 v[56:57], s[4:5], 0, v[64:65]
	v_lshl_add_u64 v[64:65], s[0:1], 0, v[64:65]
	s_cmp_lg_u32 16, -1
	s_cselect_b32 s16, 16, 0
	s_mov_b32 s17, s7
	s_mov_b32 s18, s7
	s_mov_b32 s19, s7
	s_mov_b32 s20, s7
	s_waitcnt vmcnt(3)
	ds_write_b128 v84, v[0:3]
	s_waitcnt vmcnt(2)
	ds_write_b128 v85, v[4:7]
	s_waitcnt vmcnt(1)
	ds_write_b128 v24, v[8:11] offset:49152
	v_and_b32_e32 v8, 0x70, v52
	v_lshlrev_b32_e32 v0, 8, v18
	v_bitop3_b32 v182, v176, v8, v19 bitop3:0x36
	v_bitop3_b32 v188, v21, v0, v17 bitop3:0xde
	v_add_u32_e32 v185, v182, v190
	v_add_u32_e32 v0, 16, v188
	v_add_u32_e32 v4, 16, v185
	s_waitcnt vmcnt(0)
	ds_write_b128 v0, v[12:15] offset:49152
	s_waitcnt lgkmcnt(0)
	s_barrier
	ds_read_b128 v[0:3], v4 offset:49152
	ds_read_b128 v[4:7], v4 offset:57344
	v_or_b32_e32 v9, v176, v19
	v_bitop3_b32 v187, v9, v8, 32 bitop3:0x36
	v_add_u32_e32 v189, v187, v190
	s_waitcnt lgkmcnt(0)
	v_mfma_f32_32x32x16_bf16 v[16:31], v[4:7], v[124:127], 0
	v_add_u32_e32 v4, 16, v189
	v_bitop3_b32 v193, v9, v8, s3 bitop3:0x36
	v_bitop3_b32 v191, v9, v8, 64 bitop3:0x36
	v_add_u32_e32 v194, v193, v190
	v_add_u32_e32 v192, v191, v190
	v_add_u32_e32 v8, 16, v194
	v_and_b32_e32 v5, 0x3fffffc0, v174
	v_mfma_f32_32x32x16_bf16 v[32:47], v[0:3], v[124:127], 0
	ds_read_b128 v[0:3], v4 offset:49152
	v_and_b32_e32 v11, 0xc0, v52
	v_add_u32_e32 v13, 16, v192
	ds_read_b128 v[52:55], v8 offset:57344
	v_lshl_add_u32 v177, v5, 2, s50
	ds_read_b128 v[4:7], v4 offset:57344
	v_lshlrev_b32_e32 v10, 3, v86
	s_waitcnt lgkmcnt(2)
	v_mfma_f32_32x32x16_bf16 v[32:47], v[0:3], v[120:123], v[32:47]
	v_lshlrev_b32_e32 v0, 1, v174
	v_and_b32_e32 v12, 32, v0
	ds_read_b128 v[0:3], v13 offset:49152
	v_and_or_b32 v11, v10, 24, v11
	s_mov_b32 s21, s7
	s_mov_b32 s22, s7
	s_mov_b32 s23, s7
	s_waitcnt lgkmcnt(0)
	v_mfma_f32_32x32x16_bf16 v[32:47], v[0:3], v[116:119], v[32:47]
	ds_read_b128 v[0:3], v8 offset:49152
	s_mov_b32 s24, s7
	s_mov_b32 s25, s7
	s_mov_b32 s26, s7
	s_mov_b32 s27, s7
	s_mov_b32 s28, s7
	s_mov_b32 s29, s7
	v_mfma_f32_32x32x16_bf16 v[16:31], v[4:7], v[120:123], v[16:31]
	v_and_b32_e32 v4, 0x100, v10
	v_lshlrev_b32_e32 v4, 3, v4
	v_or3_b32 v178, v11, v12, v4
	ds_read_b128 v[4:7], v13 offset:57344
	v_add_u32_e32 v181, s16, v178
	s_mov_b32 s16, s7
	s_mov_b32 s30, s7
	s_mov_b32 s31, s7
	s_waitcnt lgkmcnt(0)
	v_mfma_f32_32x32x16_bf16 v[16:31], v[4:7], v[116:119], v[16:31]
	v_lshl_add_u32 v179, v173, 2, v177
	v_mov_b32_e32 v196, 1.0
	v_mov_b32_e32 v180, 0
	v_mfma_f32_32x32x16_bf16 v[32:47], v[0:3], v[112:115], v[32:47]
	v_mov_b64_e32 v[0:1], s[16:17]
	v_mov_b64_e32 v[14:15], s[30:31]
	v_mov_b64_e32 v[2:3], s[18:19]
	v_mov_b64_e32 v[4:5], s[20:21]
	v_mov_b64_e32 v[6:7], s[22:23]
	v_mov_b64_e32 v[8:9], s[24:25]
	v_mov_b64_e32 v[10:11], s[26:27]
	v_mfma_f32_32x32x16_bf16 v[16:31], v[52:55], v[112:115], v[16:31]
	s_nop 3
	v_max_f32_e32 v52, v33, v33
	v_max_f32_e32 v53, v32, v32
	v_max_f32_e32 v52, v53, v52
	v_max3_f32 v52, v52, v34, v35
	v_max3_f32 v52, v52, v36, v37
	v_max3_f32 v52, v52, v38, v39
	v_max3_f32 v52, v52, v40, v41
	v_max3_f32 v52, v52, v42, v43
	v_max3_f32 v52, v52, v44, v45
	v_max3_f32 v66, v52, v46, v47
	v_lshl_add_u64 v[52:53], s[4:5], 0, v[60:61]
	v_lshl_add_u64 v[60:61], s[0:1], 0, v[60:61]
	global_load_dwordx4 v[52:55], v[52:53], off
	s_nop 0
	global_load_dwordx4 v[56:59], v[56:57], off
	v_mov_b64_e32 v[12:13], s[28:29]
	global_load_dwordx4 v[60:63], v[60:61], off
	s_mov_b32 s19, 1
	global_load_dwordx4 v[80:83], v[64:65], off
	v_max3_f32 v64, v66, v16, v17
	v_max3_f32 v64, v64, v18, v19
	v_max3_f32 v64, v64, v20, v21
	v_max3_f32 v64, v64, v22, v23
	v_max3_f32 v64, v64, v24, v25
	v_max3_f32 v64, v64, v26, v27
	v_max3_f32 v64, v64, v28, v29
	v_max3_f32 v70, v64, v30, v31
	v_lshl_add_u64 v[64:65], v[50:51], 0, s[40:41]
	v_lshl_add_u64 v[66:67], s[0:1], 0, v[64:65]
	v_lshl_add_u64 v[50:51], v[50:51], 0, s[44:45]
	v_lshl_add_u64 v[64:65], s[4:5], 0, v[64:65]
	v_lshl_add_u64 v[68:69], s[0:1], 0, v[50:51]
	global_load_dwordx4 v[136:139], v[66:67], off
	global_load_dwordx4 v[128:131], v[68:69], off
	v_lshl_add_u64 v[50:51], s[4:5], 0, v[50:51]
	global_load_dwordx4 v[140:143], v[64:65], off
	global_load_dwordx4 v[132:135], v[50:51], off
	v_mov_b32_e32 v71, v70
	s_nop 1
	v_permlane32_swap_b32_e32 v70, v71
	v_max_f32_e32 v50, v71, v71
	v_max_f32_e32 v51, v70, v70
	v_max_f32_e32 v50, v51, v50
	v_sub_f32_e32 v64, v16, v50
	v_add_u32_e32 v16, s58, v183
	v_sub_f32_e32 v32, v32, v50
	v_sub_f32_e32 v33, v33, v50
	v_sub_f32_e32 v34, v34, v50
	v_sub_f32_e32 v35, v35, v50
	v_sub_f32_e32 v36, v36, v50
	v_sub_f32_e32 v37, v37, v50
	v_sub_f32_e32 v38, v38, v50
	v_sub_f32_e32 v39, v39, v50
	v_sub_f32_e32 v40, v40, v50
	v_sub_f32_e32 v41, v41, v50
	v_sub_f32_e32 v42, v42, v50
	v_sub_f32_e32 v43, v43, v50
	v_sub_f32_e32 v44, v44, v50
	v_sub_f32_e32 v45, v45, v50
	v_sub_f32_e32 v46, v46, v50
	v_sub_f32_e32 v47, v47, v50
	v_sub_f32_e32 v66, v18, v50
	s_waitcnt vmcnt(4)
	s_waitcnt vmcnt(7)
	ds_write_b128 v84, v[52:55] offset:16384
	s_waitcnt vmcnt(6)
	ds_write_b128 v85, v[56:59] offset:16384
	v_and_b32_e32 v18, 15, v174
	s_waitcnt vmcnt(5)
	ds_write_b128 v16, v[60:63]
	v_add_u32_e32 v16, s58, v188
	v_sub_f32_e32 v65, v17, v50
	v_exp_f32_e32 v152, v32
	v_exp_f32_e32 v153, v33
	v_exp_f32_e32 v154, v34
	v_exp_f32_e32 v155, v35
	v_exp_f32_e32 v156, v36
	v_exp_f32_e32 v157, v37
	v_exp_f32_e32 v158, v38
	v_exp_f32_e32 v159, v39
	v_exp_f32_e32 v144, v40
	v_exp_f32_e32 v145, v41
	v_exp_f32_e32 v146, v42
	v_exp_f32_e32 v147, v43
	v_exp_f32_e32 v148, v44
	v_exp_f32_e32 v149, v45
	v_exp_f32_e32 v150, v46
	v_exp_f32_e32 v151, v47
	s_waitcnt vmcnt(4)
	ds_write_b128 v16, v[80:83]
	v_lshl_add_u64 v[16:17], s[6:7], 0, v[48:49]
	v_lshlrev_b32_e32 v18, 4, v18
	v_or3_b32 v16, v16, s66, v18
	v_add_f32_e32 v195, 0, v50
	v_xor_b32_e32 v248, 0x80000000, v195
	v_mov_b32_e32 v249, v248
	v_sub_f32_e32 v79, v31, v50
	v_sub_f32_e32 v78, v30, v50
	v_sub_f32_e32 v77, v29, v50
	v_sub_f32_e32 v76, v28, v50
	v_sub_f32_e32 v75, v27, v50
	v_sub_f32_e32 v74, v26, v50
	v_sub_f32_e32 v73, v25, v50
	v_sub_f32_e32 v72, v24, v50
	v_sub_f32_e32 v71, v23, v50
	v_sub_f32_e32 v70, v22, v50
	v_sub_f32_e32 v69, v21, v50
	v_sub_f32_e32 v68, v20, v50
	v_sub_f32_e32 v67, v19, v50
	v_lshl_add_u64 v[166:167], s[12:13], 0, v[16:17]
	v_mov_b64_e32 v[62:63], v[14:15]
	v_mov_b64_e32 v[46:47], v[14:15]
	v_mov_b64_e32 v[30:31], v[14:15]
	v_cmp_gt_u32_e64 s[0:1], 32, v86
	v_mov_b64_e32 v[60:61], v[12:13]
	v_mov_b64_e32 v[58:59], v[10:11]
	v_mov_b64_e32 v[56:57], v[8:9]
	v_mov_b64_e32 v[54:55], v[6:7]
	v_mov_b64_e32 v[52:53], v[4:5]
	v_mov_b64_e32 v[50:51], v[2:3]
	v_mov_b64_e32 v[48:49], v[0:1]
	v_mov_b64_e32 v[44:45], v[12:13]
	v_mov_b64_e32 v[42:43], v[10:11]
	v_mov_b64_e32 v[40:41], v[8:9]
	v_mov_b64_e32 v[38:39], v[6:7]
	v_mov_b64_e32 v[36:37], v[4:5]
	v_mov_b64_e32 v[34:35], v[2:3]
	v_mov_b64_e32 v[32:33], v[0:1]
	v_mov_b64_e32 v[28:29], v[12:13]
	v_mov_b64_e32 v[26:27], v[10:11]
	v_mov_b64_e32 v[24:25], v[8:9]
	v_mov_b64_e32 v[22:23], v[6:7]
	v_mov_b64_e32 v[20:21], v[4:5]
	v_mov_b64_e32 v[18:19], v[2:3]
	v_mov_b64_e32 v[16:17], v[0:1]
	s_mov_b32 s6, 1
	s_mov_b32 s18, 0
	s_waitcnt lgkmcnt(0)
	s_barrier
	v_add_co_u32_e32 v242, vcc, s61, v166
	s_nop 1
	v_addc_co_u32_e32 v243, vcc, -1, v167, vcc
	s_nop 0
	v_readfirstlane_b32 s98, v242
	v_readfirstlane_b32 s99, v243
	s_nop 1
	v_subrev_u32_e32 v242, s98, v242
	v_add_u32_e32 v243, 0x8000, v242
	v_add_u32_e32 v244, 0x1000000, v242
	v_add_u32_e32 v245, 0x1008000, v242
.LBB0_423:
	s_lshl_b32 s16, s19, 14
	s_add_i32 s4, s16, 16
	v_add_u32_e32 v96, s4, v185
	ds_read_b128 v[198:201], v96 offset:49152
	ds_read_b128 v[202:205], v96 offset:57344
	v_mov_b64_e32 v[80:81], v[248:249]
	v_mov_b64_e32 v[82:83], v[80:81]
	v_mov_b64_e32 v[84:85], v[80:81]
	v_mov_b64_e32 v[86:87], v[80:81]
	v_mov_b64_e32 v[88:89], v[80:81]
	v_mov_b64_e32 v[90:91], v[80:81]
	v_mov_b64_e32 v[92:93], v[80:81]
	v_mov_b64_e32 v[94:95], v[80:81]
	v_exp_f32_e32 v221, v64
	s_waitcnt lgkmcnt(1)
	v_mfma_f32_32x32x16_bf16 v[96:111], v[198:201], v[124:127], v[80:95]
	v_add_f32_e32 v64, v153, v152
	v_add_f32_e32 v64, v154, v64
	v_add_u32_e32 v197, s4, v189
	v_add_f32_e32 v64, v155, v64
	v_add_f32_e32 v64, v156, v64
	v_add_f32_e32 v64, v157, v64
	v_add_f32_e32 v64, v158, v64
	s_waitcnt lgkmcnt(0)
	v_mfma_f32_32x32x16_bf16 v[80:95], v[202:205], v[124:127], v[80:95]
	ds_read_b128 v[198:201], v197 offset:49152
	ds_read_b128 v[202:205], v197 offset:57344
	v_add_f32_e32 v64, v159, v64
	v_add_f32_e32 v64, v144, v64
	v_add_f32_e32 v64, v145, v64
	v_add_f32_e32 v64, v146, v64
	v_add_u32_e32 v197, s4, v192
	v_add_f32_e32 v64, v147, v64
	s_waitcnt lgkmcnt(1)
	v_mfma_f32_32x32x16_bf16 v[96:111], v[198:201], v[120:123], v[96:111]
	ds_read_b128 v[198:201], v197 offset:49152
	ds_read_b128 v[206:209], v197 offset:57344
	v_add_f32_e32 v64, v148, v64
	v_exp_f32_e32 v222, v65
	v_add_f32_e32 v64, v149, v64
	v_exp_f32_e32 v223, v66
	v_add_f32_e32 v64, v150, v64
	v_exp_f32_e32 v224, v67
	s_waitcnt lgkmcnt(2)
	v_mfma_f32_32x32x16_bf16 v[80:95], v[202:205], v[120:123], v[80:95]
	v_add_f32_e32 v64, v151, v64
	v_add_f32_e32 v64, v221, v64
	v_add_f32_e32 v64, v222, v64
	v_add_f32_e32 v64, v223, v64
	v_exp_f32_e32 v71, v71
	v_add_f32_e32 v64, v224, v64
	v_add_u32_e32 v197, s4, v194
	s_waitcnt lgkmcnt(1)
	v_mfma_f32_32x32x16_bf16 v[96:111], v[198:201], v[116:119], v[96:111]
	v_exp_f32_e32 v199, v68
	v_exp_f32_e32 v200, v69
	v_exp_f32_e32 v201, v70
	v_exp_f32_e32 v225, v72
	v_add_f32_e32 v64, v199, v64
	ds_read_b128 v[202:205], v197 offset:49152
	ds_read_b128 v[210:213], v197 offset:57344
	v_exp_f32_e32 v226, v73
	s_waitcnt lgkmcnt(2)
	v_mfma_f32_32x32x16_bf16 v[80:95], v[206:209], v[116:119], v[80:95]
	v_add_f32_e32 v64, v200, v64
	v_exp_f32_e32 v227, v74
	v_add_f32_e32 v64, v201, v64
	v_exp_f32_e32 v206, v75
	v_add_f32_e32 v64, v71, v64
	v_exp_f32_e32 v207, v76
	v_add_f32_e32 v64, v225, v64
	v_exp_f32_e32 v208, v77
	v_add_f32_e32 v64, v226, v64
	v_exp_f32_e32 v209, v78
	s_waitcnt lgkmcnt(1)
	v_mfma_f32_32x32x16_bf16 v[96:111], v[202:205], v[112:115], v[96:111]
	v_add_f32_e32 v64, v227, v64
	v_exp_f32_e32 v79, v79
	v_add_f32_e32 v64, v206, v64
	v_add_f32_e32 v64, v207, v64
	v_add_f32_e32 v64, v208, v64
	v_add_f32_e32 v64, v209, v64
	v_add_f32_e32 v197, v79, v64
	s_waitcnt lgkmcnt(0)
	v_mfma_f32_32x32x16_bf16 v[80:95], v[210:213], v[112:115], v[80:95]
	v_cvt_pk_bf16_f32 v64, v152, v153
	v_cvt_pk_bf16_f32 v65, v154, v155
	v_cvt_pk_bf16_f32 v66, v156, v157
	v_cvt_pk_bf16_f32 v67, v158, v159
	v_cvt_pk_bf16_f32 v72, v144, v145
	v_cvt_pk_bf16_f32 v73, v146, v147
	v_cvt_pk_bf16_f32 v74, v148, v149
	v_cvt_pk_bf16_f32 v75, v150, v151
	v_cvt_pk_bf16_f32 v68, v221, v222
	v_cvt_pk_bf16_f32 v69, v223, v224
	v_cvt_pk_bf16_f32 v70, v199, v200
	v_cvt_pk_bf16_f32 v71, v201, v71
	v_cvt_pk_bf16_f32 v76, v225, v226
	v_cvt_pk_bf16_f32 v77, v227, v206
	v_cvt_pk_bf16_f32 v78, v207, v208
	v_cvt_pk_bf16_f32 v79, v209, v79
	global_load_dwordx4 v[144:147], v244, s[98:99]
	global_load_dwordx4 v[148:151], v245, s[98:99]
	global_load_dwordx4 v[152:155], v242, s[98:99]
	global_load_dwordx4 v[156:159], v243, s[98:99]
	s_add_u32 s98, s98, 0x10000
	s_addc_u32 s99, s99, 0
	v_lshl_add_u32 v199, s18, 14, v181
	ds_read_b64_tr_b16 v[200:201], v199 offset:0
	ds_read_b64_tr_b16 v[202:203], v199 offset:0x100
	ds_read_b64_tr_b16 v[204:205], v199 offset:0x1000
	ds_read_b64_tr_b16 v[206:207], v199 offset:0x1100
	ds_read_b64_tr_b16 v[208:209], v199 offset:0x2000
	ds_read_b64_tr_b16 v[210:211], v199 offset:0x2100
	ds_read_b64_tr_b16 v[222:223], v199 offset:0x3000
	ds_read_b64_tr_b16 v[224:225], v199 offset:0x3100
	s_waitcnt lgkmcnt(6)
	v_mfma_f32_32x32x16_bf16 v[0:15], v[64:67], v[200:203], v[0:15]
	v_max_f32_e32 v200, v96, v97
	v_max3_f32 v200, v200, v98, v99
	v_max3_f32 v200, v200, v100, v101
	v_max3_f32 v200, v200, v102, v103
	v_max3_f32 v200, v200, v104, v105
	s_waitcnt lgkmcnt(4)
	v_mfma_f32_32x32x16_bf16 v[0:15], v[72:75], v[204:207], v[0:15]
	v_max3_f32 v200, v200, v106, v107
	v_max3_f32 v202, v200, v108, v109
	ds_read_b64_tr_b16 v[200:201], v199 offset:0x200
	v_max3_f32 v212, v202, v110, v111
	ds_read_b64_tr_b16 v[202:203], v199 offset:0x300
	ds_read_b64_tr_b16 v[204:205], v199 offset:0x1200
	ds_read_b64_tr_b16 v[206:207], v199 offset:0x1300
	s_waitcnt lgkmcnt(6)
	v_mfma_f32_32x32x16_bf16 v[0:15], v[68:71], v[208:211], v[0:15]
	ds_read_b64_tr_b16 v[208:209], v199 offset:0x2200
	ds_read_b64_tr_b16 v[210:211], v199 offset:0x2300
	ds_read_b64_tr_b16 v[226:227], v199 offset:0x3200
	ds_read_b64_tr_b16 v[228:229], v199 offset:0x3300
	s_waitcnt lgkmcnt(8)
	v_mfma_f32_32x32x16_bf16 v[0:15], v[76:79], v[222:225], v[0:15]
	s_waitcnt lgkmcnt(6)
	v_mfma_f32_32x32x16_bf16 v[48:63], v[64:67], v[200:203], v[48:63]
	v_max3_f32 v212, v212, v80, v81
	v_max3_f32 v200, v212, v82, v83
	ds_read_b64_tr_b16 v[202:203], v199 offset:0x400
	v_max3_f32 v200, v200, v84, v85
	v_max3_f32 v200, v200, v86, v87
	v_max3_f32 v200, v200, v88, v89
	v_max3_f32 v200, v200, v90, v91
	s_waitcnt lgkmcnt(5)
	v_mfma_f32_32x32x16_bf16 v[48:63], v[72:75], v[204:207], v[48:63]
	ds_read_b64_tr_b16 v[204:205], v199 offset:0x500
	ds_read_b64_tr_b16 v[206:207], v199 offset:0x1400
	v_max3_f32 v200, v200, v92, v93
	v_max3_f32 v200, v200, v94, v95
	s_waitcnt lgkmcnt(5)
	v_mfma_f32_32x32x16_bf16 v[48:63], v[68:71], v[208:211], v[48:63]
	ds_read_b64_tr_b16 v[208:209], v199 offset:0x1500
	ds_read_b64_tr_b16 v[210:211], v199 offset:0x2400
	ds_read_b64_tr_b16 v[212:213], v199 offset:0x2500
	ds_read_b64_tr_b16 v[222:223], v199 offset:0x3400
	ds_read_b64_tr_b16 v[224:225], v199 offset:0x3500
	s_waitcnt lgkmcnt(8)
	v_mfma_f32_32x32x16_bf16 v[48:63], v[76:79], v[226:229], v[48:63]
	s_waitcnt lgkmcnt(6)
	v_mfma_f32_32x32x16_bf16 v[32:47], v[64:67], v[202:205], v[32:47]
	v_cmp_ge_f32_e32 vcc, s63, v200
	s_cmp_eq_u64 vcc, exec
	s_waitcnt lgkmcnt(4)
	v_mfma_f32_32x32x16_bf16 v[32:47], v[72:75], v[206:209], v[32:47]
	s_waitcnt lgkmcnt(2)
	v_mfma_f32_32x32x16_bf16 v[32:47], v[68:71], v[210:213], v[32:47]
	s_waitcnt lgkmcnt(0)
	v_mfma_f32_32x32x16_bf16 v[32:47], v[76:79], v[222:225], v[32:47]
	s_cbranch_scc0 .LBB0_438
	v_mov_b32_e32 v200, 1.0
	s_mov_b64 s[100:101], 0

.LBB0_429:
	v_exp_f32_e32 v199, v96
	v_exp_f32_e32 v221, v97
	v_exp_f32_e32 v226, v98
	v_exp_f32_e32 v227, v99
	v_exp_f32_e32 v228, v100
	v_exp_f32_e32 v229, v101
	v_exp_f32_e32 v230, v102
	v_exp_f32_e32 v231, v103
	v_exp_f32_e32 v232, v104
	v_exp_f32_e32 v233, v105
	v_exp_f32_e32 v234, v106
	v_exp_f32_e32 v235, v107
	v_exp_f32_e32 v236, v108
	v_exp_f32_e32 v237, v109
	v_exp_f32_e32 v238, v110
	v_exp_f32_e32 v239, v111
	s_waitcnt lgkmcnt(0)
	s_barrier
	v_add_u32_e32 v96, s17, v185
	ds_read_b128 v[202:205], v96 offset:49152
	ds_read_b128 v[206:209], v96 offset:57344
	v_mov_b64_e32 v[64:65], v[248:249]
	v_mov_b64_e32 v[66:67], v[64:65]
	v_mov_b64_e32 v[68:69], v[64:65]
	v_mov_b64_e32 v[70:71], v[64:65]
	v_mov_b64_e32 v[72:73], v[64:65]
	v_mov_b64_e32 v[74:75], v[64:65]
	v_mov_b64_e32 v[76:77], v[64:65]
	v_mov_b64_e32 v[78:79], v[64:65]
	v_add_u32_e32 v201, s17, v189
	v_exp_f32_e32 v80, v80
	s_waitcnt lgkmcnt(1)
	v_mfma_f32_32x32x16_bf16 v[96:111], v[202:205], v[124:127], v[64:79]
	v_exp_f32_e32 v81, v81
	v_exp_f32_e32 v82, v82
	v_exp_f32_e32 v83, v83
	v_exp_f32_e32 v84, v84
	v_exp_f32_e32 v85, v85
	v_exp_f32_e32 v86, v86
	v_exp_f32_e32 v87, v87
	s_waitcnt lgkmcnt(0)
	v_mfma_f32_32x32x16_bf16 v[64:79], v[206:209], v[124:127], v[64:79]
	ds_read_b128 v[202:205], v201 offset:49152
	ds_read_b128 v[206:209], v201 offset:57344
	v_add_u32_e32 v201, s17, v192
	v_exp_f32_e32 v240, v91
	v_exp_f32_e32 v241, v92
	v_cvt_pk_bf16_f32 v91, v230, v231
	v_cvt_pk_bf16_f32 v92, v232, v233
	s_waitcnt lgkmcnt(1)
	v_mfma_f32_32x32x16_bf16 v[96:111], v[202:205], v[120:123], v[96:111]
	ds_read_b128 v[202:205], v201 offset:49152
	ds_read_b128 v[210:213], v201 offset:57344
	v_add_u32_e32 v201, s17, v194
	s_waitcnt lgkmcnt(1)
	v_mfma_f32_32x32x16_bf16 v[96:111], v[202:205], v[116:119], v[96:111]
	v_exp_f32_e32 v203, v88
	v_add_f32_e32 v88, v221, v199
	v_add_f32_e32 v88, v226, v88
	v_add_f32_e32 v88, v227, v88
	v_add_f32_e32 v88, v228, v88
	v_add_f32_e32 v88, v229, v88
	v_add_f32_e32 v88, v230, v88
	v_add_f32_e32 v88, v231, v88
	v_add_f32_e32 v88, v232, v88
	v_add_f32_e32 v88, v233, v88
	v_mfma_f32_32x32x16_bf16 v[64:79], v[206:209], v[120:123], v[64:79]
	v_add_f32_e32 v88, v234, v88
	v_add_f32_e32 v88, v235, v88
	v_add_f32_e32 v88, v236, v88
	v_add_f32_e32 v88, v237, v88
	v_add_f32_e32 v88, v238, v88
	v_add_f32_e32 v88, v239, v88
	v_add_f32_e32 v88, v80, v88
	v_add_f32_e32 v88, v81, v88
	s_waitcnt lgkmcnt(0)
	v_mfma_f32_32x32x16_bf16 v[64:79], v[210:213], v[116:119], v[64:79]
	v_add_f32_e32 v88, v82, v88
	v_add_f32_e32 v88, v83, v88
	v_add_f32_e32 v88, v84, v88
	ds_read_b128 v[206:209], v201 offset:49152
	ds_read_b128 v[222:225], v201 offset:57344
	v_exp_f32_e32 v204, v89
	v_add_f32_e32 v88, v85, v88
	v_exp_f32_e32 v205, v90
	v_add_f32_e32 v88, v86, v88
	v_add_f32_e32 v88, v87, v88
	v_add_f32_e32 v88, v203, v88
	v_exp_f32_e32 v210, v93
	v_add_f32_e32 v88, v204, v88
	v_exp_f32_e32 v211, v94
	s_waitcnt lgkmcnt(1)
	v_mfma_f32_32x32x16_bf16 v[96:111], v[206:209], v[112:115], v[96:111]
	v_add_f32_e32 v88, v205, v88
	v_exp_f32_e32 v212, v95
	v_add_f32_e32 v88, v240, v88
	v_add_f32_e32 v88, v241, v88
	v_add_f32_e32 v88, v210, v88
	v_add_f32_e32 v88, v211, v88
	v_add_f32_e32 v201, v212, v88
	s_waitcnt lgkmcnt(0)
	v_mfma_f32_32x32x16_bf16 v[64:79], v[222:225], v[112:115], v[64:79]
	v_cvt_pk_bf16_f32 v88, v199, v221
	v_cvt_pk_bf16_f32 v89, v226, v227
	v_cvt_pk_bf16_f32 v90, v228, v229
	v_cvt_pk_bf16_f32 v93, v234, v235
	v_cvt_pk_bf16_f32 v94, v236, v237
	v_cvt_pk_bf16_f32 v95, v238, v239
	v_cvt_pk_bf16_f32 v80, v80, v81
	v_cvt_pk_bf16_f32 v81, v82, v83
	v_cvt_pk_bf16_f32 v82, v84, v85
	v_cvt_pk_bf16_f32 v83, v86, v87
	v_cvt_pk_bf16_f32 v84, v203, v204
	v_cvt_pk_bf16_f32 v85, v205, v240
	v_cvt_pk_bf16_f32 v86, v241, v210
	v_cvt_pk_bf16_f32 v87, v211, v212
	s_cmpk_gt_u32 s6, 0x7c
	s_cselect_b64 s[4:5], -1, 0
	s_and_b64 vcc, exec, s[4:5]
	s_cbranch_vccnz .Lattn_a0_lastw
	global_load_dwordx4 v[132:135], v244, s[98:99]
	global_load_dwordx4 v[128:131], v242, s[98:99]
	global_load_dwordx4 v[140:143], v245, s[98:99]
	global_load_dwordx4 v[136:139], v243, s[98:99]
	s_add_u32 s98, s98, 0x10000
	s_addc_u32 s99, s99, 0

.LBB0_438:
	v_mov_b32_e32 v201, v200
	s_nop 1
	v_permlane32_swap_b32_e32 v200, v201
	v_max_f32_e32 v200, v200, v201
	v_max_f32_e32 v202, 0, v200
	v_exp_f32_e64 v200, -v202
	v_add_f32_e32 v195, v195, v202
	v_xor_b32_e32 v248, 0x80000000, v195
	v_mov_b32_e32 v249, v248
	v_pk_add_f32 v[96:97], v[96:97], v[202:203] op_sel_hi:[1,0] neg_lo:[0,1] neg_hi:[0,1]
	v_pk_add_f32 v[98:99], v[98:99], v[202:203] op_sel_hi:[1,0] neg_lo:[0,1] neg_hi:[0,1]
	v_pk_add_f32 v[100:101], v[100:101], v[202:203] op_sel_hi:[1,0] neg_lo:[0,1] neg_hi:[0,1]
	v_pk_add_f32 v[102:103], v[102:103], v[202:203] op_sel_hi:[1,0] neg_lo:[0,1] neg_hi:[0,1]
	v_pk_add_f32 v[104:105], v[104:105], v[202:203] op_sel_hi:[1,0] neg_lo:[0,1] neg_hi:[0,1]
	v_pk_add_f32 v[106:107], v[106:107], v[202:203] op_sel_hi:[1,0] neg_lo:[0,1] neg_hi:[0,1]
	v_pk_add_f32 v[108:109], v[108:109], v[202:203] op_sel_hi:[1,0] neg_lo:[0,1] neg_hi:[0,1]
	v_pk_add_f32 v[110:111], v[110:111], v[202:203] op_sel_hi:[1,0] neg_lo:[0,1] neg_hi:[0,1]
	v_sub_f32_e32 v95, v95, v202
	v_sub_f32_e32 v94, v94, v202
	v_sub_f32_e32 v93, v93, v202
	v_sub_f32_e32 v92, v92, v202
	v_sub_f32_e32 v91, v91, v202
	v_sub_f32_e32 v90, v90, v202
	v_sub_f32_e32 v89, v89, v202
	v_sub_f32_e32 v88, v88, v202
	v_sub_f32_e32 v87, v87, v202
	v_sub_f32_e32 v86, v86, v202
	v_sub_f32_e32 v85, v85, v202
	v_sub_f32_e32 v84, v84, v202
	v_sub_f32_e32 v83, v83, v202
	v_sub_f32_e32 v82, v82, v202
	v_sub_f32_e32 v81, v81, v202
	v_sub_f32_e32 v80, v80, v202
	v_cmp_gt_f32_e64 s[100:101], 1.0, v200
	s_branch .LBB0_425
.LBB0_439:
	v_mov_b32_e32 v199, v204
	s_nop 1
	v_permlane32_swap_b32_e32 v204, v199
	v_max_f32_e32 v199, v204, v199
	v_max_f32_e32 v204, 0, v199
	v_exp_f32_e64 v199, -v204
	v_add_f32_e32 v195, v195, v204
	v_xor_b32_e32 v248, 0x80000000, v195
	v_mov_b32_e32 v249, v248
	v_pk_add_f32 v[96:97], v[96:97], v[204:205] op_sel_hi:[1,0] neg_lo:[0,1] neg_hi:[0,1]
	v_pk_add_f32 v[98:99], v[98:99], v[204:205] op_sel_hi:[1,0] neg_lo:[0,1] neg_hi:[0,1]
	v_pk_add_f32 v[100:101], v[100:101], v[204:205] op_sel_hi:[1,0] neg_lo:[0,1] neg_hi:[0,1]
	v_pk_add_f32 v[102:103], v[102:103], v[204:205] op_sel_hi:[1,0] neg_lo:[0,1] neg_hi:[0,1]
	v_pk_add_f32 v[104:105], v[104:105], v[204:205] op_sel_hi:[1,0] neg_lo:[0,1] neg_hi:[0,1]
	v_pk_add_f32 v[106:107], v[106:107], v[204:205] op_sel_hi:[1,0] neg_lo:[0,1] neg_hi:[0,1]
	v_pk_add_f32 v[108:109], v[108:109], v[204:205] op_sel_hi:[1,0] neg_lo:[0,1] neg_hi:[0,1]
	v_pk_add_f32 v[110:111], v[110:111], v[204:205] op_sel_hi:[1,0] neg_lo:[0,1] neg_hi:[0,1]
	v_sub_f32_e32 v79, v79, v204
	v_sub_f32_e32 v78, v78, v204
	v_sub_f32_e32 v77, v77, v204
	v_sub_f32_e32 v76, v76, v204
	v_sub_f32_e32 v75, v75, v204
	v_sub_f32_e32 v74, v74, v204
	v_sub_f32_e32 v73, v73, v204
	v_sub_f32_e32 v72, v72, v204
	v_sub_f32_e32 v71, v71, v204
	v_sub_f32_e32 v70, v70, v204
	v_sub_f32_e32 v69, v69, v204
	v_sub_f32_e32 v68, v68, v204
	v_sub_f32_e32 v67, v67, v204
	v_sub_f32_e32 v66, v66, v204
	v_sub_f32_e32 v65, v65, v204
	v_sub_f32_e32 v64, v64, v204
	v_cmp_gt_f32_e64 s[100:101], 1.0, v199
	s_branch .LBB0_432

.LBB0_805:
	s_lshl_b32 s0, s39, 10
	s_and_b32 s6, s0, 0x800000
	s_lshl_b32 s0, s43, 1
	s_and_b32 s65, s0, 0x300
	s_lshl_b32 s0, s2, 11
	s_lshl_b32 s1, s2, 4
	s_and_b32 s0, s0, 0x2000
	s_and_b32 s1, s1, 0xffffff80
	s_add_i32 s1, s0, s1
	v_or_b32_e32 v171, s1, v170
	v_or_b32_e32 v0, v171, v169
	v_ashrrev_i32_e32 v1, 31, v0
	s_lshl_b32 s1, s2, 7
	v_lshlrev_b64 v[0:1], 10, v[0:1]
	s_and_b32 s64, s1, 0x180
	v_lshl_add_u64 v[0:1], s[86:87], 0, v[0:1]
	s_lshl_b32 s4, s64, 1
	s_mov_b32 s5, s7
	v_lshl_add_u64 v[0:1], v[0:1], 0, s[4:5]
	s_lshl_b32 s5, s0, 10
	s_add_u32 s0, s33, s5
	s_addc_u32 s1, s34, 0
	s_add_u32 s0, s0, s4
	v_mov_b32_e32 v174, v168
	v_lshl_add_u64 v[0:1], v[160:161], 1, v[0:1]
	s_addc_u32 s1, s1, 0
	v_lshl_add_u64 v[0:1], v[0:1], 0, v[162:163]
	v_ashrrev_i32_e32 v16, 4, v174
	s_add_u32 s5, s35, s5
	v_lshlrev_b32_e32 v20, 3, v174
	v_add_u32_e32 v18, 32, v16
	s_addc_u32 s16, s38, 0
	global_load_dwordx4 v[124:127], v[0:1], off
	global_load_dwordx4 v[120:123], v[0:1], off offset:32
	global_load_dwordx4 v[116:119], v[0:1], off offset:64
	global_load_dwordx4 v[112:115], v[0:1], off offset:96
	v_and_b32_e32 v0, 0x78, v20
	v_ashrrev_i32_e32 v17, 31, v16
	v_ashrrev_i32_e32 v19, 31, v18
	s_add_u32 s4, s5, s4
	v_lshlrev_b32_e32 v21, 1, v0
	v_lshlrev_b64 v[48:49], 10, v[16:17]
	v_lshlrev_b64 v[12:13], 10, v[18:19]
	s_addc_u32 s5, s16, 0
	v_or_b32_e32 v50, v48, v21
	v_mov_b32_e32 v51, v49
	v_or_b32_e32 v12, v12, v21
	v_lshl_add_u64 v[0:1], s[4:5], 0, v[50:51]
	v_lshl_add_u64 v[4:5], s[4:5], 0, v[12:13]
	s_barrier
	global_load_dwordx4 v[0:3], v[0:1], off
	s_nop 0
	global_load_dwordx4 v[4:7], v[4:5], off
	v_lshl_add_u64 v[8:9], s[0:1], 0, v[50:51]
	global_load_dwordx4 v[8:11], v[8:9], off
	v_lshl_add_u64 v[12:13], s[0:1], 0, v[12:13]
	global_load_dwordx4 v[12:15], v[12:13], off
	v_and_b32_e32 v22, 0xfffff0, v16
	v_lshlrev_b32_e32 v23, 1, v16
	v_lshrrev_b32_e32 v24, 1, v16
	v_and_b32_e32 v25, 3, v16
	v_and_or_b32 v22, v23, 8, v22
	v_and_or_b32 v23, v24, 4, v25
	v_and_b32_e32 v24, 0xfffff0, v18
	v_lshlrev_b32_e32 v25, 1, v18
	v_and_b32_e32 v17, 0x70, v174
	v_bfe_u32 v20, v20, 5, 2
	v_lshlrev_b32_e32 v16, 8, v16
	v_lshrrev_b32_e32 v22, 1, v22
	v_and_or_b32 v24, v25, 8, v24
	v_bitop3_b32 v183, v21, v16, v17 bitop3:0xde
	v_or_b32_e32 v16, v22, v20
	v_lshrrev_b32_e32 v22, 1, v24
	v_lshlrev_b32_e32 v23, 6, v23
	v_and_b32_e32 v26, 48, v21
	v_lshlrev_b32_e32 v16, 9, v16
	v_or_b32_e32 v20, v22, v20
	v_or3_b32 v184, v16, v23, v26
	v_lshlrev_b32_e32 v16, 9, v20
	v_bfe_u32 v172, v174, 5, 1
	v_ashrrev_i32_e32 v175, 8, v174
	v_lshlrev_b32_e32 v52, 4, v174
	v_or3_b32 v186, v16, v23, v26
	v_add_u32_e32 v84, 16, v184
	v_and_b32_e32 v173, 31, v174
	v_lshlrev_b32_e32 v19, 7, v175
	v_add_u32_e32 v24, 16, v183
	v_add_u32_e32 v85, 16, v186
	s_waitcnt vmcnt(0)
	v_lshlrev_b32_e32 v176, 4, v172
	v_lshlrev_b32_e32 v190, 8, v173
	v_and_b32_e32 v86, 63, v174
	v_lshl_add_u64 v[60:61], v[50:51], 0, s[14:15]
	v_lshl_add_u64 v[64:65], v[50:51], 0, s[36:37]
	v_lshl_add_u64 v[56:57], s[4:5], 0, v[64:65]
	v_lshl_add_u64 v[64:65], s[0:1], 0, v[64:65]
	s_cmp_lg_u32 16, -1
	s_cselect_b32 s16, 16, 0
	s_mov_b32 s17, s7
	s_mov_b32 s18, s7
	s_mov_b32 s19, s7
	s_mov_b32 s20, s7
	s_waitcnt vmcnt(3)
	ds_write_b128 v84, v[0:3]
	s_waitcnt vmcnt(2)
	ds_write_b128 v85, v[4:7]
	s_waitcnt vmcnt(1)
	ds_write_b128 v24, v[8:11] offset:49152
	v_and_b32_e32 v8, 0x70, v52
	v_lshlrev_b32_e32 v0, 8, v18
	v_bitop3_b32 v182, v176, v8, v19 bitop3:0x36
	v_bitop3_b32 v188, v21, v0, v17 bitop3:0xde
	v_add_u32_e32 v185, v182, v190
	v_add_u32_e32 v0, 16, v188
	v_add_u32_e32 v4, 16, v185
	s_waitcnt vmcnt(0)
	ds_write_b128 v0, v[12:15] offset:49152
	s_waitcnt lgkmcnt(0)
	s_barrier
	ds_read_b128 v[0:3], v4 offset:49152
	ds_read_b128 v[4:7], v4 offset:57344
	v_or_b32_e32 v9, v176, v19
	v_bitop3_b32 v187, v9, v8, 32 bitop3:0x36
	v_add_u32_e32 v189, v187, v190
	s_waitcnt lgkmcnt(0)
	v_mfma_f32_32x32x16_bf16 v[16:31], v[4:7], v[124:127], 0
	v_add_u32_e32 v4, 16, v189
	v_bitop3_b32 v193, v9, v8, s3 bitop3:0x36
	v_bitop3_b32 v191, v9, v8, 64 bitop3:0x36
	v_add_u32_e32 v194, v193, v190
	v_add_u32_e32 v192, v191, v190
	v_add_u32_e32 v8, 16, v194
	v_and_b32_e32 v5, 0x3fffffc0, v174
	v_mfma_f32_32x32x16_bf16 v[32:47], v[0:3], v[124:127], 0
	ds_read_b128 v[0:3], v4 offset:49152
	v_and_b32_e32 v11, 0xc0, v52
	v_add_u32_e32 v13, 16, v192
	ds_read_b128 v[52:55], v8 offset:57344
	v_lshl_add_u32 v177, v5, 2, s50
	ds_read_b128 v[4:7], v4 offset:57344
	v_lshlrev_b32_e32 v10, 3, v86
	s_waitcnt lgkmcnt(2)
	v_mfma_f32_32x32x16_bf16 v[32:47], v[0:3], v[120:123], v[32:47]
	v_lshlrev_b32_e32 v0, 1, v174
	v_and_b32_e32 v12, 32, v0
	ds_read_b128 v[0:3], v13 offset:49152
	v_and_or_b32 v11, v10, 24, v11
	s_mov_b32 s21, s7
	s_mov_b32 s22, s7
	s_mov_b32 s23, s7
	s_waitcnt lgkmcnt(0)
	v_mfma_f32_32x32x16_bf16 v[32:47], v[0:3], v[116:119], v[32:47]
	ds_read_b128 v[0:3], v8 offset:49152
	s_mov_b32 s24, s7
	s_mov_b32 s25, s7
	s_mov_b32 s26, s7
	s_mov_b32 s27, s7
	s_mov_b32 s28, s7
	s_mov_b32 s29, s7
	v_mfma_f32_32x32x16_bf16 v[16:31], v[4:7], v[120:123], v[16:31]
	v_and_b32_e32 v4, 0x100, v10
	v_lshlrev_b32_e32 v4, 3, v4
	v_or3_b32 v178, v11, v12, v4
	ds_read_b128 v[4:7], v13 offset:57344
	v_add_u32_e32 v181, s16, v178
	s_mov_b32 s16, s7
	s_mov_b32 s30, s7
	s_mov_b32 s31, s7
	s_waitcnt lgkmcnt(0)
	v_mfma_f32_32x32x16_bf16 v[16:31], v[4:7], v[116:119], v[16:31]
	v_lshl_add_u32 v179, v173, 2, v177
	v_mov_b32_e32 v196, 1.0
	v_mov_b32_e32 v180, 0
	v_mfma_f32_32x32x16_bf16 v[32:47], v[0:3], v[112:115], v[32:47]
	v_mov_b64_e32 v[0:1], s[16:17]
	v_mov_b64_e32 v[14:15], s[30:31]
	v_mov_b64_e32 v[2:3], s[18:19]
	v_mov_b64_e32 v[4:5], s[20:21]
	v_mov_b64_e32 v[6:7], s[22:23]
	v_mov_b64_e32 v[8:9], s[24:25]
	v_mov_b64_e32 v[10:11], s[26:27]
	v_mfma_f32_32x32x16_bf16 v[16:31], v[52:55], v[112:115], v[16:31]
	s_nop 3
	v_max_f32_e32 v52, v33, v33
	v_max_f32_e32 v53, v32, v32
	v_max_f32_e32 v52, v53, v52
	v_max3_f32 v52, v52, v34, v35
	v_max3_f32 v52, v52, v36, v37
	v_max3_f32 v52, v52, v38, v39
	v_max3_f32 v52, v52, v40, v41
	v_max3_f32 v52, v52, v42, v43
	v_max3_f32 v52, v52, v44, v45
	v_max3_f32 v66, v52, v46, v47
	v_lshl_add_u64 v[52:53], s[4:5], 0, v[60:61]
	v_lshl_add_u64 v[60:61], s[0:1], 0, v[60:61]
	global_load_dwordx4 v[52:55], v[52:53], off
	s_nop 0
	global_load_dwordx4 v[56:59], v[56:57], off
	v_mov_b64_e32 v[12:13], s[28:29]
	global_load_dwordx4 v[60:63], v[60:61], off
	s_mov_b32 s19, 1
	global_load_dwordx4 v[80:83], v[64:65], off
	v_max3_f32 v64, v66, v16, v17
	v_max3_f32 v64, v64, v18, v19
	v_max3_f32 v64, v64, v20, v21
	v_max3_f32 v64, v64, v22, v23
	v_max3_f32 v64, v64, v24, v25
	v_max3_f32 v64, v64, v26, v27
	v_max3_f32 v64, v64, v28, v29
	v_max3_f32 v70, v64, v30, v31
	v_lshl_add_u64 v[64:65], v[50:51], 0, s[40:41]
	v_lshl_add_u64 v[66:67], s[0:1], 0, v[64:65]
	v_lshl_add_u64 v[50:51], v[50:51], 0, s[44:45]
	v_lshl_add_u64 v[64:65], s[4:5], 0, v[64:65]
	v_lshl_add_u64 v[68:69], s[0:1], 0, v[50:51]
	global_load_dwordx4 v[136:139], v[66:67], off
	global_load_dwordx4 v[128:131], v[68:69], off
	v_lshl_add_u64 v[50:51], s[4:5], 0, v[50:51]
	global_load_dwordx4 v[140:143], v[64:65], off
	global_load_dwordx4 v[132:135], v[50:51], off
	v_mov_b32_e32 v71, v70
	s_nop 1
	v_permlane32_swap_b32_e32 v70, v71
	v_max_f32_e32 v50, v71, v71
	v_max_f32_e32 v51, v70, v70
	v_max_f32_e32 v50, v51, v50
	v_sub_f32_e32 v64, v16, v50
	v_add_u32_e32 v16, s58, v183
	v_sub_f32_e32 v32, v32, v50
	v_sub_f32_e32 v33, v33, v50
	v_sub_f32_e32 v34, v34, v50
	v_sub_f32_e32 v35, v35, v50
	v_sub_f32_e32 v36, v36, v50
	v_sub_f32_e32 v37, v37, v50
	v_sub_f32_e32 v38, v38, v50
	v_sub_f32_e32 v39, v39, v50
	v_sub_f32_e32 v40, v40, v50
	v_sub_f32_e32 v41, v41, v50
	v_sub_f32_e32 v42, v42, v50
	v_sub_f32_e32 v43, v43, v50
	v_sub_f32_e32 v44, v44, v50
	v_sub_f32_e32 v45, v45, v50
	v_sub_f32_e32 v46, v46, v50
	v_sub_f32_e32 v47, v47, v50
	v_sub_f32_e32 v66, v18, v50
	s_waitcnt vmcnt(4)
	s_waitcnt vmcnt(7)
	ds_write_b128 v84, v[52:55] offset:16384
	s_waitcnt vmcnt(6)
	ds_write_b128 v85, v[56:59] offset:16384
	v_and_b32_e32 v18, 15, v174
	s_waitcnt vmcnt(5)
	ds_write_b128 v16, v[60:63]
	v_add_u32_e32 v16, s58, v188
	v_sub_f32_e32 v65, v17, v50
	v_exp_f32_e32 v152, v32
	v_exp_f32_e32 v153, v33
	v_exp_f32_e32 v154, v34
	v_exp_f32_e32 v155, v35
	v_exp_f32_e32 v156, v36
	v_exp_f32_e32 v157, v37
	v_exp_f32_e32 v158, v38
	v_exp_f32_e32 v159, v39
	v_exp_f32_e32 v144, v40
	v_exp_f32_e32 v145, v41
	v_exp_f32_e32 v146, v42
	v_exp_f32_e32 v147, v43
	v_exp_f32_e32 v148, v44
	v_exp_f32_e32 v149, v45
	v_exp_f32_e32 v150, v46
	v_exp_f32_e32 v151, v47
	s_waitcnt vmcnt(4)
	ds_write_b128 v16, v[80:83]
	v_lshl_add_u64 v[16:17], s[6:7], 0, v[48:49]
	v_lshlrev_b32_e32 v18, 4, v18
	v_or3_b32 v16, v16, s65, v18
	v_add_f32_e32 v195, 0, v50
	v_xor_b32_e32 v248, 0x80000000, v195
	v_mov_b32_e32 v249, v248
	v_sub_f32_e32 v79, v31, v50
	v_sub_f32_e32 v78, v30, v50
	v_sub_f32_e32 v77, v29, v50
	v_sub_f32_e32 v76, v28, v50
	v_sub_f32_e32 v75, v27, v50
	v_sub_f32_e32 v74, v26, v50
	v_sub_f32_e32 v73, v25, v50
	v_sub_f32_e32 v72, v24, v50
	v_sub_f32_e32 v71, v23, v50
	v_sub_f32_e32 v70, v22, v50
	v_sub_f32_e32 v69, v21, v50
	v_sub_f32_e32 v68, v20, v50
	v_sub_f32_e32 v67, v19, v50
	v_lshl_add_u64 v[166:167], s[12:13], 0, v[16:17]
	v_mov_b64_e32 v[62:63], v[14:15]
	v_mov_b64_e32 v[46:47], v[14:15]
	v_mov_b64_e32 v[30:31], v[14:15]
	v_cmp_gt_u32_e64 s[0:1], 32, v86
	v_mov_b64_e32 v[60:61], v[12:13]
	v_mov_b64_e32 v[58:59], v[10:11]
	v_mov_b64_e32 v[56:57], v[8:9]
	v_mov_b64_e32 v[54:55], v[6:7]
	v_mov_b64_e32 v[52:53], v[4:5]
	v_mov_b64_e32 v[50:51], v[2:3]
	v_mov_b64_e32 v[48:49], v[0:1]
	v_mov_b64_e32 v[44:45], v[12:13]
	v_mov_b64_e32 v[42:43], v[10:11]
	v_mov_b64_e32 v[40:41], v[8:9]
	v_mov_b64_e32 v[38:39], v[6:7]
	v_mov_b64_e32 v[36:37], v[4:5]
	v_mov_b64_e32 v[34:35], v[2:3]
	v_mov_b64_e32 v[32:33], v[0:1]
	v_mov_b64_e32 v[28:29], v[12:13]
	v_mov_b64_e32 v[26:27], v[10:11]
	v_mov_b64_e32 v[24:25], v[8:9]
	v_mov_b64_e32 v[22:23], v[6:7]
	v_mov_b64_e32 v[20:21], v[4:5]
	v_mov_b64_e32 v[18:19], v[2:3]
	v_mov_b64_e32 v[16:17], v[0:1]
	s_mov_b32 s6, 1
	s_mov_b32 s18, 0
	s_waitcnt lgkmcnt(0)
	s_barrier
	v_add_co_u32_e32 v242, vcc, s61, v166
	s_nop 1
	v_addc_co_u32_e32 v243, vcc, -1, v167, vcc
	s_nop 0
	v_readfirstlane_b32 s98, v242
	v_readfirstlane_b32 s99, v243
	s_nop 1
	v_subrev_u32_e32 v242, s98, v242
	v_add_u32_e32 v243, 0x8000, v242
	v_add_u32_e32 v244, 0x1000000, v242
	v_add_u32_e32 v245, 0x1008000, v242
